# phase 3: every other group of eight workgroups runs its sample conv unit before its prompt unit
# speedup vs baseline: 1.0131x; 1.0043x over previous
.LBB0_292:
.LBB0_293:
	s_cmp_lt_i32 s68, 4
	s_cselect_b64 s[8:9], -1, 0
	s_and_b64 s[18:19], s[8:9], s[6:7]
	s_andn2_b64 vcc, exec, s[18:19]
	s_cbranch_vccnz .LBB0_510
	s_cmpk_gt_i32 s2, 0x1ff
	s_cbranch_scc1 .LBB0_510
	v_bfe_u32 v113, v1, 5, 1
	v_lshl_or_b32 v3, v1, 8, v1
	v_lshlrev_b32_e32 v4, 14, v113
	s_movk_i32 s8, 0x403
	v_and_or_b32 v121, v3, s8, v4
	v_bfe_u32 v4, v1, 3, 3
	v_and_b32_e32 v2, 63, v1
	v_and_b32_e32 v111, 31, v1
	v_bitop3_b32 v5, v4, v1, 7 bitop3:0x78
	v_lshlrev_b32_e32 v4, 7, v4
	v_and_b32_e32 v3, 7, v1
	v_lshl_or_b32 v106, v5, 4, v4
	v_lshlrev_b32_e32 v4, 7, v111
	v_cmp_lt_u32_e64 s[8:9], 31, v2
	v_bitop3_b32 v2, v113, v1, 7 bitop3:0x78
	v_lshl_or_b32 v154, v2, 4, v4
	v_bitop3_b32 v2, v113, v3, 2 bitop3:0x36
	v_lshl_or_b32 v156, v2, 4, v4
	v_bitop3_b32 v2, v113, v3, 4 bitop3:0x36
	v_lshl_or_b32 v157, v2, 4, v4
	v_bitop3_b32 v2, v113, v3, 6 bitop3:0x36
	v_lshl_or_b32 v158, v2, 4, v4
	v_add_u32_e32 v2, 0x200, v1
	v_mov_b32_e32 v109, 0
	v_lshlrev_b32_e32 v112, 3, v2
	v_lshrrev_b32_e32 v162, 2, v2
	v_lshlrev_b32_e32 v2, 1, v1
	s_movk_i32 s10, 0x80
	v_mov_b32_e32 v107, v109
	v_and_or_b32 v164, v2, s10, v111
	v_lshlrev_b32_e32 v2, 2, v113
	v_lshlrev_b32_e32 v110, 3, v1
	v_lshl_or_b32 v2, v164, 5, v2
	s_add_u32 s97, s66, 0x3c00000
	v_lshl_add_u64 v[4:5], s[66:67], 0, v[106:107]
	s_mov_b64 s[22:23], 0x8000
	s_mov_b32 s0, s3
	v_cmp_gt_u32_e64 s[6:7], 8, v111
	v_lshlrev_b32_e32 v120, 3, v113
	v_or_b32_e32 v122, 0x800, v121
	s_movk_i32 s96, 0x1000
	v_or_b32_e32 v123, 0x1000, v121
	v_or_b32_e32 v124, 0x1800, v121
	v_or_b32_e32 v125, 0x2000, v121
	v_or_b32_e32 v126, 0x2800, v121
	v_or_b32_e32 v127, 0x3000, v121
	v_or_b32_e32 v128, 0x3800, v121
	v_or_b32_e32 v129, 0x8000, v121
	v_or_b32_e32 v130, 0x8800, v121
	v_or_b32_e32 v131, 0x9000, v121
	v_or_b32_e32 v132, 0x9800, v121
	v_or_b32_e32 v133, 0xa000, v121
	v_or_b32_e32 v134, 0xa800, v121
	v_or_b32_e32 v135, 0xb000, v121
	v_or_b32_e32 v136, 0xb800, v121
	v_or_b32_e32 v137, 0x10000, v121
	v_or_b32_e32 v138, 0x10800, v121
	v_or_b32_e32 v139, 0x11000, v121
	v_or_b32_e32 v140, 0x11800, v121
	v_or_b32_e32 v141, 0x12000, v121
	v_or_b32_e32 v142, 0x12800, v121
	v_or_b32_e32 v143, 0x13000, v121
	v_or_b32_e32 v144, 0x13800, v121
	v_or_b32_e32 v145, 0x18000, v121
	v_or_b32_e32 v146, 0x18800, v121
	v_or_b32_e32 v147, 0x19000, v121
	v_or_b32_e32 v148, 0x19800, v121
	v_or_b32_e32 v149, 0x1a000, v121
	v_or_b32_e32 v150, 0x1a800, v121
	v_or_b32_e32 v151, 0x1b000, v121
	v_or_b32_e32 v152, 0x1b800, v121
	v_lshrrev_b32_e32 v153, 6, v1
	v_or_b32_e32 v155, 2, v113
	v_add_u32_e32 v159, 8, v110
	v_lshrrev_b32_e32 v160, 2, v1
	v_add_u32_e32 v161, 8, v112
	v_lshrrev_b32_e32 v163, 7, v1
	s_addc_u32 s3, s67, 0
	v_lshlrev_b32_e32 v165, 1, v111
	s_mov_b32 s21, 0
	v_sub_u32_e32 v166, 0, v111
	v_lshl_add_u64 v[114:115], v[4:5], 0, s[22:23]
	v_lshl_add_u32 v167, v1, 4, 0
	s_movk_i32 s1, 0x100
	s_mov_b32 s74, 0x447fc000
	v_mov_b32_e32 v168, 0xc0447cbd
	s_mov_b32 s75, 0xbfb8aa3b
	s_mov_b32 s76, 0x1a40000
	s_mov_b64 s[24:25], 0x400
	s_mov_b64 s[26:27], 0x800
	s_mov_b64 s[28:29], 0xc00
	s_movk_i32 s77, 0x79c0
	v_mov_b32_e32 v169, 0x4000
	v_mov_b32_e32 v170, 0x7000
	v_mov_b32_e32 v171, 0x5000
	v_mov_b32_e32 v172, 0x8000
	v_lshlrev_b32_e32 v116, 1, v112
	v_mov_b32_e32 v173, 0x3000
	v_mov_b32_e32 v174, 0x6000
	v_lshlrev_b32_e32 v118, 1, v2
	v_mov_b32_e32 v190, v109
	v_mov_b32_e32 v191, v109
	v_mov_b32_e32 v192, v109
	v_mov_b32_e32 v193, v109
	s_mov_b32 s78, s2
	s_mov_b32 s32, s70
	s_cmpk_lg_u32 s70, 0x100
	s_cbranch_scc1 .Lp3_order
	s_bitcmp1_b32 s2, 3
	s_cbranch_scc0 .Lp3_order
	s_addk_i32 s78, 0x100
	s_movk_i32 s32, 0xff00

.LBB0_296:
	s_or_b64 exec, exec, s[10:11]
	s_waitcnt vmcnt(0)
	v_lshlrev_b32_e32 v70, 16, v66
	v_and_b32_e32 v66, 0xffff0000, v66
	v_mov_b32_e32 v72, v66
	v_and_b32_e32 v91, 16, v68
	v_and_b32_e32 v90, 0xffff0000, v67
	v_lshlrev_b32_e32 v67, 16, v67
	v_pk_mul_f32 v[72:73], v[84:85], v[72:73]
	v_mov_b32_e32 v74, v85
	v_mov_b32_e32 v75, v85
	v_mov_b32_e32 v78, v84
	v_mov_b32_e32 v79, v84
	v_pk_fma_f32 v[72:73], v[84:85], v[70:71], v[72:73] op_sel:[0,0,1] op_sel_hi:[1,0,0]
	v_pk_mov_b32 v[84:85], v[66:67], v[90:91] op_sel:[1,0]
	v_mov_b32_e32 v81, v80
	v_pk_mul_f32 v[84:85], v[78:79], v[84:85]
	v_and_b32_e32 v83, 0xffff0000, v69
	v_and_b32_e32 v87, 16, v69
	v_and_b32_e32 v86, 0xffff0000, v68
	v_lshlrev_b32_e32 v89, 16, v69
	v_lshlrev_b32_e32 v69, 16, v68
	v_mov_b32_e32 v68, v90
	v_pk_fma_f32 v[72:73], v[80:81], v[66:67], v[72:73]
	v_pk_fma_f32 v[66:67], v[74:75], v[66:67], v[84:85]
	v_mov_b32_e32 v77, v76
	v_pk_fma_f32 v[66:67], v[80:81], v[68:69], v[66:67]
	v_mov_b32_e32 v88, v86
	v_pk_add_f32 v[84:85], v[76:77], v[66:67]
	v_pk_mov_b32 v[66:67], v[68:69], v[86:87] op_sel:[1,0]
	v_mov_b32_e32 v82, v89
	v_pk_mul_f32 v[66:67], v[78:79], v[66:67]
	v_mov_b32_e32 v70, v83
	v_pk_fma_f32 v[66:67], v[74:75], v[68:69], v[66:67]
	v_pk_add_f32 v[72:73], v[76:77], v[72:73]
	v_pk_fma_f32 v[66:67], v[80:81], v[88:89], v[66:67]
	v_add_lshl_u32 v108, s79, v163, 15
	v_pk_add_f32 v[68:69], v[76:77], v[66:67]
	v_pk_mul_f32 v[66:67], v[78:79], v[82:83]
	v_cvt_pk_bf16_f32 v68, v68, v69
	v_pk_fma_f32 v[66:67], v[74:75], v[88:89], v[66:67]
	v_add_u32_e32 v78, v182, v120
	v_pk_fma_f32 v[66:67], v[80:81], v[70:71], v[66:67]
	v_mov_b32_e32 v119, v109
	v_pk_add_f32 v[70:71], v[76:77], v[66:67]
	v_cvt_pk_bf16_f32 v66, v72, v73
	v_cvt_pk_bf16_f32 v67, v84, v85
	v_cvt_pk_bf16_f32 v69, v70, v71
	ds_write_b128 v183, v[66:69]
	v_lshlrev_b32_e32 v68, 2, v180
	v_lshl_add_u32 v70, v180, 6, v78
	v_and_b32_e32 v71, 48, v68
	v_add_u32_e32 v68, v70, v71
	s_waitcnt lgkmcnt(0)
	s_barrier
	ds_read_b64 v[68:69], v68
	v_xad_u32 v72, v71, 16, v70
	v_xad_u32 v73, v71, 32, v70
	v_xad_u32 v74, v71, 48, v70
	v_lshl_add_u64 v[66:67], s[64:65], 0, v[108:109]
	ds_read_b64 v[70:71], v72
	ds_read_b64 v[72:73], v73
	ds_read_b64 v[74:75], v74
	s_waitcnt lgkmcnt(3)
	v_lshlrev_b32_e32 v76, 16, v68
	v_and_b32_e32 v77, 0xffff0000, v68
	v_lshlrev_b32_e32 v68, 16, v69
	v_and_b32_e32 v69, 0xffff0000, v69
	v_lshl_add_u64 v[66:67], v[66:67], 0, s[20:21]
	v_pk_mul_f32 v[2:3], v[2:3], v[76:77]
	v_pk_mul_f32 v[4:5], v[4:5], v[68:69]
	v_cvt_pk_bf16_f32 v2, v2, v3
	v_cvt_pk_bf16_f32 v3, v4, v5
	v_lshl_add_u64 v[4:5], v[66:67], 0, v[118:119]
	global_store_dwordx2 v[4:5], v[2:3], off
	s_waitcnt lgkmcnt(2)
	v_lshlrev_b32_e32 v2, 16, v70
	v_and_b32_e32 v3, 0xffff0000, v70
	v_pk_mul_f32 v[2:3], v[6:7], v[2:3]
	v_lshlrev_b32_e32 v6, 16, v71
	v_and_b32_e32 v7, 0xffff0000, v71
	v_pk_mul_f32 v[6:7], v[8:9], v[6:7]
	v_cvt_pk_bf16_f32 v2, v2, v3
	v_cvt_pk_bf16_f32 v3, v6, v7
	global_store_dwordx2 v[4:5], v[2:3], off offset:16
	s_waitcnt lgkmcnt(1)
	v_lshlrev_b32_e32 v2, 16, v72
	v_and_b32_e32 v3, 0xffff0000, v72
	v_lshlrev_b32_e32 v6, 16, v73
	v_and_b32_e32 v7, 0xffff0000, v73
	v_pk_mul_f32 v[2:3], v[10:11], v[2:3]
	v_pk_mul_f32 v[6:7], v[12:13], v[6:7]
	v_cvt_pk_bf16_f32 v2, v2, v3
	v_cvt_pk_bf16_f32 v3, v6, v7
	s_and_b64 s[10:11], s[30:31], exec
	global_store_dwordx2 v[4:5], v[2:3], off offset:32
	s_waitcnt lgkmcnt(0)
	v_lshlrev_b32_e32 v2, 16, v74
	v_and_b32_e32 v3, 0xffff0000, v74
	v_lshlrev_b32_e32 v6, 16, v75
	v_and_b32_e32 v7, 0xffff0000, v75
	s_cselect_b32 s10, 60, 32
	v_pk_mul_f32 v[2:3], v[14:15], v[2:3]
	v_pk_mul_f32 v[6:7], v[16:17], v[6:7]
	v_cvt_pk_bf16_f32 v2, v2, v3
	v_cvt_pk_bf16_f32 v3, v6, v7
	v_add_u32_e32 v14, s10, v180
	global_store_dwordx2 v[4:5], v[2:3], off offset:48
	v_lshlrev_b32_e32 v2, 2, v14
	v_lshl_add_u32 v6, v14, 6, v78
	v_and_b32_e32 v7, 48, v2
	v_add_u32_e32 v2, v6, v7
	ds_read_b64 v[2:3], v2
	v_xad_u32 v8, v7, 16, v6
	v_xad_u32 v9, v7, 32, v6
	v_xad_u32 v10, v7, 48, v6
	ds_read_b64 v[6:7], v8
	ds_read_b64 v[8:9], v9
	ds_read_b64 v[10:11], v10
	s_waitcnt lgkmcnt(3)
	v_lshlrev_b32_e32 v12, 16, v2
	v_and_b32_e32 v13, 0xffff0000, v2
	v_pk_mul_f32 v[12:13], v[18:19], v[12:13]
	v_add_u32_e32 v14, s10, v14
	v_cvt_pk_bf16_f32 v2, v12, v13
	v_lshlrev_b32_e32 v12, 16, v3
	v_and_b32_e32 v13, 0xffff0000, v3
	v_pk_mul_f32 v[12:13], v[20:21], v[12:13]
	s_add_i32 s78, s78, s32
	v_cvt_pk_bf16_f32 v3, v12, v13
	global_store_dwordx2 v[4:5], v[2:3], off offset:2048
	s_waitcnt lgkmcnt(2)
	v_lshlrev_b32_e32 v2, 16, v6
	v_and_b32_e32 v3, 0xffff0000, v6
	v_lshlrev_b32_e32 v6, 16, v7
	v_and_b32_e32 v7, 0xffff0000, v7
	v_pk_mul_f32 v[2:3], v[22:23], v[2:3]
	v_pk_mul_f32 v[6:7], v[24:25], v[6:7]
	v_cvt_pk_bf16_f32 v2, v2, v3
	v_cvt_pk_bf16_f32 v3, v6, v7
	global_store_dwordx2 v[4:5], v[2:3], off offset:2064
	s_waitcnt lgkmcnt(1)
	v_lshlrev_b32_e32 v2, 16, v8
	v_and_b32_e32 v3, 0xffff0000, v8
	v_lshlrev_b32_e32 v6, 16, v9
	v_and_b32_e32 v7, 0xffff0000, v9
	v_pk_mul_f32 v[2:3], v[26:27], v[2:3]
	v_pk_mul_f32 v[6:7], v[28:29], v[6:7]
	v_cvt_pk_bf16_f32 v2, v2, v3
	v_cvt_pk_bf16_f32 v3, v6, v7
	global_store_dwordx2 v[4:5], v[2:3], off offset:2080
	s_waitcnt lgkmcnt(0)
	v_lshlrev_b32_e32 v2, 16, v10
	v_and_b32_e32 v3, 0xffff0000, v10
	v_lshlrev_b32_e32 v6, 16, v11
	v_and_b32_e32 v7, 0xffff0000, v11
	v_pk_mul_f32 v[2:3], v[30:31], v[2:3]
	v_pk_mul_f32 v[6:7], v[32:33], v[6:7]
	v_cvt_pk_bf16_f32 v2, v2, v3
	v_cvt_pk_bf16_f32 v3, v6, v7
	global_store_dwordx2 v[4:5], v[2:3], off offset:2096
	v_lshlrev_b32_e32 v2, 2, v14
	v_lshl_add_u32 v6, v14, 6, v78
	v_and_b32_e32 v7, 48, v2
	v_add_u32_e32 v2, v6, v7
	ds_read_b64 v[2:3], v2
	v_xad_u32 v8, v7, 16, v6
	v_xad_u32 v9, v7, 32, v6
	v_xad_u32 v10, v7, 48, v6
	ds_read_b64 v[6:7], v8
	ds_read_b64 v[8:9], v9
	ds_read_b64 v[10:11], v10
	s_waitcnt lgkmcnt(3)
	v_lshlrev_b32_e32 v12, 16, v2
	v_and_b32_e32 v13, 0xffff0000, v2
	v_pk_mul_f32 v[12:13], v[34:35], v[12:13]
	v_add_co_u32_e32 v4, vcc, s96, v4
	v_cvt_pk_bf16_f32 v2, v12, v13
	v_lshlrev_b32_e32 v12, 16, v3
	v_and_b32_e32 v13, 0xffff0000, v3
	v_pk_mul_f32 v[12:13], v[36:37], v[12:13]
	v_addc_co_u32_e32 v5, vcc, 0, v5, vcc
	v_cvt_pk_bf16_f32 v3, v12, v13
	global_store_dwordx2 v[4:5], v[2:3], off
	s_waitcnt lgkmcnt(2)
	v_lshlrev_b32_e32 v2, 16, v6
	v_and_b32_e32 v3, 0xffff0000, v6
	v_lshlrev_b32_e32 v6, 16, v7
	v_and_b32_e32 v7, 0xffff0000, v7
	v_pk_mul_f32 v[2:3], v[38:39], v[2:3]
	v_pk_mul_f32 v[6:7], v[40:41], v[6:7]
	v_cvt_pk_bf16_f32 v2, v2, v3
	v_cvt_pk_bf16_f32 v3, v6, v7
	global_store_dwordx2 v[4:5], v[2:3], off offset:16
	s_waitcnt lgkmcnt(1)
	v_lshlrev_b32_e32 v2, 16, v8
	v_and_b32_e32 v3, 0xffff0000, v8
	v_lshlrev_b32_e32 v6, 16, v9
	v_and_b32_e32 v7, 0xffff0000, v9
	v_pk_mul_f32 v[2:3], v[42:43], v[2:3]
	v_pk_mul_f32 v[6:7], v[44:45], v[6:7]
	v_cvt_pk_bf16_f32 v2, v2, v3
	v_cvt_pk_bf16_f32 v3, v6, v7
	global_store_dwordx2 v[4:5], v[2:3], off offset:32
	s_waitcnt lgkmcnt(0)
	v_lshlrev_b32_e32 v2, 16, v10
	v_and_b32_e32 v3, 0xffff0000, v10
	v_lshlrev_b32_e32 v6, 16, v11
	v_and_b32_e32 v7, 0xffff0000, v11
	v_pk_mul_f32 v[2:3], v[46:47], v[2:3]
	v_pk_mul_f32 v[6:7], v[48:49], v[6:7]
	v_cvt_pk_bf16_f32 v2, v2, v3
	v_cvt_pk_bf16_f32 v3, v6, v7
	global_store_dwordx2 v[4:5], v[2:3], off offset:48
	v_add_u32_e32 v2, s10, v14
	v_lshl_add_u32 v6, v2, 6, v78
	v_lshlrev_b32_e32 v2, 2, v2
	v_and_b32_e32 v7, 48, v2
	v_add_u32_e32 v2, v6, v7
	ds_read_b64 v[2:3], v2
	v_xad_u32 v8, v7, 16, v6
	v_xad_u32 v9, v7, 32, v6
	v_xad_u32 v10, v7, 48, v6
	ds_read_b64 v[6:7], v8
	ds_read_b64 v[8:9], v9
	ds_read_b64 v[10:11], v10
	s_waitcnt lgkmcnt(3)
	v_lshlrev_b32_e32 v12, 16, v2
	v_and_b32_e32 v13, 0xffff0000, v2
	v_pk_mul_f32 v[12:13], v[50:51], v[12:13]
	s_cmpk_lt_u32 s78, 0x200
	v_cvt_pk_bf16_f32 v2, v12, v13
	v_lshlrev_b32_e32 v12, 16, v3
	v_and_b32_e32 v13, 0xffff0000, v3
	v_pk_mul_f32 v[12:13], v[52:53], v[12:13]
	s_nop 0
	v_cvt_pk_bf16_f32 v3, v12, v13
	global_store_dwordx2 v[4:5], v[2:3], off offset:2048
	s_waitcnt lgkmcnt(2)
	v_lshlrev_b32_e32 v2, 16, v6
	v_and_b32_e32 v3, 0xffff0000, v6
	v_lshlrev_b32_e32 v6, 16, v7
	v_and_b32_e32 v7, 0xffff0000, v7
	v_pk_mul_f32 v[2:3], v[54:55], v[2:3]
	v_pk_mul_f32 v[6:7], v[56:57], v[6:7]
	v_cvt_pk_bf16_f32 v2, v2, v3
	v_cvt_pk_bf16_f32 v3, v6, v7
	global_store_dwordx2 v[4:5], v[2:3], off offset:2064
	s_waitcnt lgkmcnt(1)
	v_lshlrev_b32_e32 v2, 16, v8
	v_and_b32_e32 v3, 0xffff0000, v8
	v_lshlrev_b32_e32 v6, 16, v9
	v_and_b32_e32 v7, 0xffff0000, v9
	v_pk_mul_f32 v[2:3], v[58:59], v[2:3]
	v_pk_mul_f32 v[6:7], v[60:61], v[6:7]
	v_cvt_pk_bf16_f32 v2, v2, v3
	v_cvt_pk_bf16_f32 v3, v6, v7
	global_store_dwordx2 v[4:5], v[2:3], off offset:2080
	s_waitcnt lgkmcnt(0)
	v_lshlrev_b32_e32 v2, 16, v10
	v_and_b32_e32 v3, 0xffff0000, v10
	v_lshlrev_b32_e32 v6, 16, v11
	v_and_b32_e32 v7, 0xffff0000, v11
	v_pk_mul_f32 v[2:3], v[62:63], v[2:3]
	v_pk_mul_f32 v[6:7], v[64:65], v[6:7]
	v_cvt_pk_bf16_f32 v2, v2, v3
	v_cvt_pk_bf16_f32 v3, v6, v7
	global_store_dwordx2 v[4:5], v[2:3], off offset:2096
	s_barrier
	s_cbranch_scc0 .LBB0_509
